# PEER pass 1 restructured: u table column-sliced per XCD (L2 resident) with partial dot products + finalize pass (sum, scales, erf gelu, gates); phase 26 runs 3 sub-passes
# speedup vs baseline: 1.0133x; 1.0133x over previous
_Z4mega6Params:
	s_mov_b64 s[74:75], s[0:1]
	v_mov_b32_e32 v251, 0
	s_load_dwordx2 s[0:1], s[74:75], 0xd0
	s_add_u32 s6, s74, 0xd0
	v_writelane_b32 v250, s2, 0
	v_and_b32_e32 v135, 0x3ff, v0
	s_addc_u32 s7, s75, 0
	s_waitcnt lgkmcnt(0)
	v_writelane_b32 v250, s0, 1
	v_cmp_gt_u32_e32 vcc, 4, v135
	s_nop 0
	v_writelane_b32 v250, s1, 2
	s_and_saveexec_b64 s[0:1], vcc
	v_lshl_add_u32 v1, v135, 2, 0
	v_add_u32_e32 v1, 0x26c00, v1
	v_mov_b32_e32 v2, 0
	ds_write_b32 v1, v2
	s_or_b64 exec, exec, s[0:1]
	s_load_dwordx2 s[2:3], s[74:75], 0xc0
	s_waitcnt lgkmcnt(0)
	s_barrier
	s_getreg_b32 s0, hwreg(HW_REG_XCC_ID, 0, 4)
	s_add_u32 s4, s2, 0x6708000
	s_addc_u32 s5, s3, 0
	s_and_b32 s12, s0, 15
	v_cmp_eq_u32_e64 s[76:77], 0, v135
	s_and_saveexec_b64 s[8:9], s[76:77]
	s_cbranch_execz .LBB0_8
	s_mov_b64 s[10:11], exec
	v_mbcnt_lo_u32_b32 v1, s10, 0
	v_mbcnt_hi_u32_b32 v1, s11, v1
	v_cmp_eq_u32_e32 vcc, 0, v1
	s_and_saveexec_b64 s[0:1], vcc
	s_cbranch_execz .LBB0_5
	s_lshl_b32 s13, s12, 8
	s_bcnt1_i32_b64 s10, s[10:11]
	v_mov_b32_e32 v1, s13
	v_mov_b32_e32 v2, s10
	global_atomic_add v1, v2, s[4:5] offset:1024

.LBB0_62:
	s_andn2_b64 vcc, exec, s[20:21]
	s_mov_b32 s24, 0x8000
	s_cbranch_vccnz .LBB0_74
	v_readlane_b32 s0, v251, 0
	s_cmp_eq_u32 s0, 0
	s_cbranch_scc1 .Lpu_pass1
	s_cmp_eq_u32 s0, 1
	s_cbranch_scc1 .Lpu_fin
	s_branch .Lpv_orig
.Lpu_pass1:
	v_and_b32_e32 v5, 7, v167
	v_lshlrev_b32_e32 v1, 4, v5
	v_lshlrev_b32_e32 v2, 5, v5
	v_lshrrev_b32_e32 v4, 3, v167
	v_lshl_or_b32 v3, v5, 3, v4
	v_lshlrev_b32_e32 v3, 2, v3
	v_lshlrev_b32_e32 v4, 2, v4
	v_lshlrev_b32_e32 v6, 2, v167
	v_mov_b32_e32 v7, 0x26c08
	ds_read_b32 v8, v7
	ds_read_b32 v9, v7 offset:4
	v_add_u32_e32 v10, 0x670b800, v6
	global_load_dword v11, v10, s[66:67] sc1
	s_waitcnt vmcnt(0) lgkmcnt(0)
	v_readfirstlane_b32 s0, v8
	v_readfirstlane_b32 s1, v9
	v_cmp_ne_u32_e64 s[20:21], 0, v11
	s_nop 3
	s_and_b32 s20, s20, 0xffff
	s_bcnt1_i32_b32 s41, s20
	s_bfm_b32 s21, s0, 0
	s_and_b32 s21, s21, s20
	s_bcnt1_i32_b32 s40, s21
	s_nop 3
	v_readlane_b32 s39, v11, s0
	v_readfirstlane_b32 s20, v135
	s_nop 3
	s_lshl_b32 s39, s39, 3
	s_max_u32 s39, s39, 8
	s_max_u32 s41, s41, 1
	s_lshr_b32 s20, s20, 6
	s_lshl_b32 s1, s1, 3
	s_add_i32 s51, s1, s20
	s_add_u32 s42, s66, 0x20b6c000
	s_addc_u32 s43, s67, 0
.Lpu_part:
	s_cmp_gt_u32 s40, 7
	s_cbranch_scc1 .Lpu_done
	s_lshl_b32 s0, s40, 21
	s_add_u32 s44, s66, s0
	s_addc_u32 s45, s67, 0
	s_add_u32 s44, s44, 0x2010000
	s_addc_u32 s45, s45, 0
	s_lshl_b32 s0, s40, 25
	s_add_u32 s46, s66, s0
	s_addc_u32 s47, s67, 0
	s_add_u32 s46, s46, 0x25f6c000
	s_addc_u32 s47, s47, 0
	s_lshl_b32 s0, s40, 8
	s_add_u32 s48, s66, s0
	s_addc_u32 s49, s67, 0
	s_add_u32 s48, s48, 0x8b6c000
	s_addc_u32 s49, s49, 0
	s_mov_b32 s38, s51
	s_min_u32 s1, s38, 0xffff
	s_lshl_b32 s0, s1, 9
	v_add_u32_e32 v120, s0, v6
	global_load_dword v10, v120, s[42:43]
	global_load_dword v11, v120, s[42:43] offset:256
	s_lshl_b32 s0, s1, 11
	v_add_u32_e32 v120, s0, v2
	global_load_dwordx4 v[20:23], v120, s[48:49]
	global_load_dwordx4 v[24:27], v120, s[48:49] offset:16
.Lpu_tok:
	s_cmp_gt_u32 s38, 0xffff
	s_cbranch_scc1 .Lpu_part_next
	s_waitcnt vmcnt(0)
	v_mov_b32_e32 v8, v10
	v_mov_b32_e32 v9, v11
	v_lshlrev_b32_e32 v28, 16, v20
	v_and_b32_e32 v29, 0xffff0000, v20
	v_lshlrev_b32_e32 v30, 16, v21
	v_and_b32_e32 v31, 0xffff0000, v21
	v_lshlrev_b32_e32 v32, 16, v22
	v_and_b32_e32 v33, 0xffff0000, v22
	v_lshlrev_b32_e32 v34, 16, v23
	v_and_b32_e32 v35, 0xffff0000, v23
	v_lshlrev_b32_e32 v36, 16, v24
	v_and_b32_e32 v37, 0xffff0000, v24
	v_lshlrev_b32_e32 v38, 16, v25
	v_and_b32_e32 v39, 0xffff0000, v25
	v_lshlrev_b32_e32 v40, 16, v26
	v_and_b32_e32 v41, 0xffff0000, v26
	v_lshlrev_b32_e32 v42, 16, v27
	v_and_b32_e32 v43, 0xffff0000, v27
	ds_bpermute_b32 v108, v4, v8
	v_add_u32_e32 v109, 32, v4
	ds_bpermute_b32 v109, v109, v8
	v_add_u32_e32 v110, 64, v4
	ds_bpermute_b32 v110, v110, v8
	v_add_u32_e32 v111, 96, v4
	ds_bpermute_b32 v111, v111, v8
	v_add_u32_e32 v112, 128, v4
	ds_bpermute_b32 v112, v112, v8
	v_add_u32_e32 v113, 160, v4
	ds_bpermute_b32 v113, v113, v8
	v_add_u32_e32 v114, 192, v4
	ds_bpermute_b32 v114, v114, v8
	v_add_u32_e32 v115, 224, v4
	ds_bpermute_b32 v115, v115, v8
	s_waitcnt lgkmcnt(0)
	v_lshl_add_u32 v108, v108, 7, v1
	v_lshl_add_u32 v109, v109, 7, v1
	v_lshl_add_u32 v110, v110, 7, v1
	v_lshl_add_u32 v111, v111, 7, v1
	v_lshl_add_u32 v112, v112, 7, v1
	v_lshl_add_u32 v113, v113, 7, v1
	v_lshl_add_u32 v114, v114, 7, v1
	v_lshl_add_u32 v115, v115, 7, v1
	global_load_dwordx4 v[44:47], v108, s[44:45]
	global_load_dwordx4 v[48:51], v109, s[44:45]
	global_load_dwordx4 v[52:55], v110, s[44:45]
	global_load_dwordx4 v[56:59], v111, s[44:45]
	global_load_dwordx4 v[60:63], v112, s[44:45]
	global_load_dwordx4 v[64:67], v113, s[44:45]
	global_load_dwordx4 v[68:71], v114, s[44:45]
	global_load_dwordx4 v[72:75], v115, s[44:45]
	ds_bpermute_b32 v108, v4, v9
	v_add_u32_e32 v109, 32, v4
	ds_bpermute_b32 v109, v109, v9
	v_add_u32_e32 v110, 64, v4
	ds_bpermute_b32 v110, v110, v9
	v_add_u32_e32 v111, 96, v4
	ds_bpermute_b32 v111, v111, v9
	v_add_u32_e32 v112, 128, v4
	ds_bpermute_b32 v112, v112, v9
	v_add_u32_e32 v113, 160, v4
	ds_bpermute_b32 v113, v113, v9
	v_add_u32_e32 v114, 192, v4
	ds_bpermute_b32 v114, v114, v9
	v_add_u32_e32 v115, 224, v4
	ds_bpermute_b32 v115, v115, v9
	s_waitcnt lgkmcnt(0)
	v_lshl_add_u32 v108, v108, 7, v1
	v_lshl_add_u32 v109, v109, 7, v1
	v_lshl_add_u32 v110, v110, 7, v1
	v_lshl_add_u32 v111, v111, 7, v1
	v_lshl_add_u32 v112, v112, 7, v1
	v_lshl_add_u32 v113, v113, 7, v1
	v_lshl_add_u32 v114, v114, 7, v1
	v_lshl_add_u32 v115, v115, 7, v1
	global_load_dwordx4 v[76:79], v108, s[44:45]
	global_load_dwordx4 v[80:83], v109, s[44:45]
	global_load_dwordx4 v[84:87], v110, s[44:45]
	global_load_dwordx4 v[88:91], v111, s[44:45]
	global_load_dwordx4 v[92:95], v112, s[44:45]
	global_load_dwordx4 v[96:99], v113, s[44:45]
	global_load_dwordx4 v[100:103], v114, s[44:45]
	global_load_dwordx4 v[104:107], v115, s[44:45]
	s_add_i32 s1, s38, s39
	s_cmp_gt_u32 s1, 0xffff
	s_cselect_b32 s1, s38, s1
	s_lshl_b32 s0, s1, 9
	v_add_u32_e32 v120, s0, v6
	global_load_dword v10, v120, s[42:43]
	global_load_dword v11, v120, s[42:43] offset:256
	s_lshl_b32 s0, s1, 11
	v_add_u32_e32 v120, s0, v2
	global_load_dwordx4 v[20:23], v120, s[48:49]
	global_load_dwordx4 v[24:27], v120, s[48:49] offset:16
	s_waitcnt vmcnt(19)
	v_cvt_pk_f32_fp8_e32 v[118:119], v44
	v_cvt_pk_f32_fp8_sdwa v[120:121], v44 src0_sel:WORD_1
	s_nop 0
	v_pk_mul_f32 v[116:117], v[118:119], v[28:29]
	v_cvt_pk_f32_fp8_e32 v[118:119], v45
	v_pk_fma_f32 v[116:117], v[120:121], v[30:31], v[116:117]
	v_cvt_pk_f32_fp8_sdwa v[120:121], v45 src0_sel:WORD_1
	v_pk_fma_f32 v[116:117], v[118:119], v[32:33], v[116:117]
	v_cvt_pk_f32_fp8_e32 v[118:119], v46
	v_pk_fma_f32 v[116:117], v[120:121], v[34:35], v[116:117]
	v_cvt_pk_f32_fp8_sdwa v[120:121], v46 src0_sel:WORD_1
	v_pk_fma_f32 v[116:117], v[118:119], v[36:37], v[116:117]
	v_cvt_pk_f32_fp8_e32 v[118:119], v47
	v_pk_fma_f32 v[116:117], v[120:121], v[38:39], v[116:117]
	v_cvt_pk_f32_fp8_sdwa v[120:121], v47 src0_sel:WORD_1
	v_pk_fma_f32 v[116:117], v[118:119], v[40:41], v[116:117]
	s_nop 0
	v_pk_fma_f32 v[116:117], v[120:121], v[42:43], v[116:117]
	v_add_f32_e32 v108, v116, v117
	s_waitcnt vmcnt(18)
	v_cvt_pk_f32_fp8_e32 v[118:119], v48
	v_cvt_pk_f32_fp8_sdwa v[120:121], v48 src0_sel:WORD_1
	s_nop 0
	v_pk_mul_f32 v[116:117], v[118:119], v[28:29]
	v_cvt_pk_f32_fp8_e32 v[118:119], v49
	v_pk_fma_f32 v[116:117], v[120:121], v[30:31], v[116:117]
	v_cvt_pk_f32_fp8_sdwa v[120:121], v49 src0_sel:WORD_1
	v_pk_fma_f32 v[116:117], v[118:119], v[32:33], v[116:117]
	v_cvt_pk_f32_fp8_e32 v[118:119], v50
	v_pk_fma_f32 v[116:117], v[120:121], v[34:35], v[116:117]
	v_cvt_pk_f32_fp8_sdwa v[120:121], v50 src0_sel:WORD_1
	v_pk_fma_f32 v[116:117], v[118:119], v[36:37], v[116:117]
	v_cvt_pk_f32_fp8_e32 v[118:119], v51
	v_pk_fma_f32 v[116:117], v[120:121], v[38:39], v[116:117]
	v_cvt_pk_f32_fp8_sdwa v[120:121], v51 src0_sel:WORD_1
	v_pk_fma_f32 v[116:117], v[118:119], v[40:41], v[116:117]
	s_nop 0
	v_pk_fma_f32 v[116:117], v[120:121], v[42:43], v[116:117]
	v_add_f32_e32 v109, v116, v117
	s_waitcnt vmcnt(17)
	v_cvt_pk_f32_fp8_e32 v[118:119], v52
	v_cvt_pk_f32_fp8_sdwa v[120:121], v52 src0_sel:WORD_1
	s_nop 0
	v_pk_mul_f32 v[116:117], v[118:119], v[28:29]
	v_cvt_pk_f32_fp8_e32 v[118:119], v53
	v_pk_fma_f32 v[116:117], v[120:121], v[30:31], v[116:117]
	v_cvt_pk_f32_fp8_sdwa v[120:121], v53 src0_sel:WORD_1
	v_pk_fma_f32 v[116:117], v[118:119], v[32:33], v[116:117]
	v_cvt_pk_f32_fp8_e32 v[118:119], v54
	v_pk_fma_f32 v[116:117], v[120:121], v[34:35], v[116:117]
	v_cvt_pk_f32_fp8_sdwa v[120:121], v54 src0_sel:WORD_1
	v_pk_fma_f32 v[116:117], v[118:119], v[36:37], v[116:117]
	v_cvt_pk_f32_fp8_e32 v[118:119], v55
	v_pk_fma_f32 v[116:117], v[120:121], v[38:39], v[116:117]
	v_cvt_pk_f32_fp8_sdwa v[120:121], v55 src0_sel:WORD_1
	v_pk_fma_f32 v[116:117], v[118:119], v[40:41], v[116:117]
	s_nop 0
	v_pk_fma_f32 v[116:117], v[120:121], v[42:43], v[116:117]
	v_add_f32_e32 v110, v116, v117
	s_waitcnt vmcnt(16)
	v_cvt_pk_f32_fp8_e32 v[118:119], v56
	v_cvt_pk_f32_fp8_sdwa v[120:121], v56 src0_sel:WORD_1
	s_nop 0
	v_pk_mul_f32 v[116:117], v[118:119], v[28:29]
	v_cvt_pk_f32_fp8_e32 v[118:119], v57
	v_pk_fma_f32 v[116:117], v[120:121], v[30:31], v[116:117]
	v_cvt_pk_f32_fp8_sdwa v[120:121], v57 src0_sel:WORD_1
	v_pk_fma_f32 v[116:117], v[118:119], v[32:33], v[116:117]
	v_cvt_pk_f32_fp8_e32 v[118:119], v58
	v_pk_fma_f32 v[116:117], v[120:121], v[34:35], v[116:117]
	v_cvt_pk_f32_fp8_sdwa v[120:121], v58 src0_sel:WORD_1
	v_pk_fma_f32 v[116:117], v[118:119], v[36:37], v[116:117]
	v_cvt_pk_f32_fp8_e32 v[118:119], v59
	v_pk_fma_f32 v[116:117], v[120:121], v[38:39], v[116:117]
	v_cvt_pk_f32_fp8_sdwa v[120:121], v59 src0_sel:WORD_1
	v_pk_fma_f32 v[116:117], v[118:119], v[40:41], v[116:117]
	s_nop 0
	v_pk_fma_f32 v[116:117], v[120:121], v[42:43], v[116:117]
	v_add_f32_e32 v111, v116, v117
	s_waitcnt vmcnt(15)
	v_cvt_pk_f32_fp8_e32 v[118:119], v60
	v_cvt_pk_f32_fp8_sdwa v[120:121], v60 src0_sel:WORD_1
	s_nop 0
	v_pk_mul_f32 v[116:117], v[118:119], v[28:29]
	v_cvt_pk_f32_fp8_e32 v[118:119], v61
	v_pk_fma_f32 v[116:117], v[120:121], v[30:31], v[116:117]
	v_cvt_pk_f32_fp8_sdwa v[120:121], v61 src0_sel:WORD_1
	v_pk_fma_f32 v[116:117], v[118:119], v[32:33], v[116:117]
	v_cvt_pk_f32_fp8_e32 v[118:119], v62
	v_pk_fma_f32 v[116:117], v[120:121], v[34:35], v[116:117]
	v_cvt_pk_f32_fp8_sdwa v[120:121], v62 src0_sel:WORD_1
	v_pk_fma_f32 v[116:117], v[118:119], v[36:37], v[116:117]
	v_cvt_pk_f32_fp8_e32 v[118:119], v63
	v_pk_fma_f32 v[116:117], v[120:121], v[38:39], v[116:117]
	v_cvt_pk_f32_fp8_sdwa v[120:121], v63 src0_sel:WORD_1
	v_pk_fma_f32 v[116:117], v[118:119], v[40:41], v[116:117]
	s_nop 0
	v_pk_fma_f32 v[116:117], v[120:121], v[42:43], v[116:117]
	v_add_f32_e32 v112, v116, v117
	s_waitcnt vmcnt(14)
	v_cvt_pk_f32_fp8_e32 v[118:119], v64
	v_cvt_pk_f32_fp8_sdwa v[120:121], v64 src0_sel:WORD_1
	s_nop 0
	v_pk_mul_f32 v[116:117], v[118:119], v[28:29]
	v_cvt_pk_f32_fp8_e32 v[118:119], v65
	v_pk_fma_f32 v[116:117], v[120:121], v[30:31], v[116:117]
	v_cvt_pk_f32_fp8_sdwa v[120:121], v65 src0_sel:WORD_1
	v_pk_fma_f32 v[116:117], v[118:119], v[32:33], v[116:117]
	v_cvt_pk_f32_fp8_e32 v[118:119], v66
	v_pk_fma_f32 v[116:117], v[120:121], v[34:35], v[116:117]
	v_cvt_pk_f32_fp8_sdwa v[120:121], v66 src0_sel:WORD_1
	v_pk_fma_f32 v[116:117], v[118:119], v[36:37], v[116:117]
	v_cvt_pk_f32_fp8_e32 v[118:119], v67
	v_pk_fma_f32 v[116:117], v[120:121], v[38:39], v[116:117]
	v_cvt_pk_f32_fp8_sdwa v[120:121], v67 src0_sel:WORD_1
	v_pk_fma_f32 v[116:117], v[118:119], v[40:41], v[116:117]
	s_nop 0
	v_pk_fma_f32 v[116:117], v[120:121], v[42:43], v[116:117]
	v_add_f32_e32 v113, v116, v117
	s_waitcnt vmcnt(13)
	v_cvt_pk_f32_fp8_e32 v[118:119], v68
	v_cvt_pk_f32_fp8_sdwa v[120:121], v68 src0_sel:WORD_1
	s_nop 0
	v_pk_mul_f32 v[116:117], v[118:119], v[28:29]
	v_cvt_pk_f32_fp8_e32 v[118:119], v69
	v_pk_fma_f32 v[116:117], v[120:121], v[30:31], v[116:117]
	v_cvt_pk_f32_fp8_sdwa v[120:121], v69 src0_sel:WORD_1
	v_pk_fma_f32 v[116:117], v[118:119], v[32:33], v[116:117]
	v_cvt_pk_f32_fp8_e32 v[118:119], v70
	v_pk_fma_f32 v[116:117], v[120:121], v[34:35], v[116:117]
	v_cvt_pk_f32_fp8_sdwa v[120:121], v70 src0_sel:WORD_1
	v_pk_fma_f32 v[116:117], v[118:119], v[36:37], v[116:117]
	v_cvt_pk_f32_fp8_e32 v[118:119], v71
	v_pk_fma_f32 v[116:117], v[120:121], v[38:39], v[116:117]
	v_cvt_pk_f32_fp8_sdwa v[120:121], v71 src0_sel:WORD_1
	v_pk_fma_f32 v[116:117], v[118:119], v[40:41], v[116:117]
	s_nop 0
	v_pk_fma_f32 v[116:117], v[120:121], v[42:43], v[116:117]
	v_add_f32_e32 v114, v116, v117
	s_waitcnt vmcnt(12)
	v_cvt_pk_f32_fp8_e32 v[118:119], v72
	v_cvt_pk_f32_fp8_sdwa v[120:121], v72 src0_sel:WORD_1
	s_nop 0
	v_pk_mul_f32 v[116:117], v[118:119], v[28:29]
	v_cvt_pk_f32_fp8_e32 v[118:119], v73
	v_pk_fma_f32 v[116:117], v[120:121], v[30:31], v[116:117]
	v_cvt_pk_f32_fp8_sdwa v[120:121], v73 src0_sel:WORD_1
	v_pk_fma_f32 v[116:117], v[118:119], v[32:33], v[116:117]
	v_cvt_pk_f32_fp8_e32 v[118:119], v74
	v_pk_fma_f32 v[116:117], v[120:121], v[34:35], v[116:117]
	v_cvt_pk_f32_fp8_sdwa v[120:121], v74 src0_sel:WORD_1
	v_pk_fma_f32 v[116:117], v[118:119], v[36:37], v[116:117]
	v_cvt_pk_f32_fp8_e32 v[118:119], v75
	v_pk_fma_f32 v[116:117], v[120:121], v[38:39], v[116:117]
	v_cvt_pk_f32_fp8_sdwa v[120:121], v75 src0_sel:WORD_1
	v_pk_fma_f32 v[116:117], v[118:119], v[40:41], v[116:117]
	s_nop 0
	v_pk_fma_f32 v[116:117], v[120:121], v[42:43], v[116:117]
	v_add_f32_e32 v115, v116, v117
	v_add_f32_dpp v108, v108, v108 quad_perm:[1,0,3,2] row_mask:0xf bank_mask:0xf
	v_add_f32_dpp v109, v109, v109 quad_perm:[1,0,3,2] row_mask:0xf bank_mask:0xf
	v_add_f32_dpp v110, v110, v110 quad_perm:[1,0,3,2] row_mask:0xf bank_mask:0xf
	v_add_f32_dpp v111, v111, v111 quad_perm:[1,0,3,2] row_mask:0xf bank_mask:0xf
	v_add_f32_dpp v112, v112, v112 quad_perm:[1,0,3,2] row_mask:0xf bank_mask:0xf
	v_add_f32_dpp v113, v113, v113 quad_perm:[1,0,3,2] row_mask:0xf bank_mask:0xf
	v_add_f32_dpp v114, v114, v114 quad_perm:[1,0,3,2] row_mask:0xf bank_mask:0xf
	v_add_f32_dpp v115, v115, v115 quad_perm:[1,0,3,2] row_mask:0xf bank_mask:0xf
	v_add_f32_dpp v108, v108, v108 quad_perm:[2,3,0,1] row_mask:0xf bank_mask:0xf
	v_add_f32_dpp v109, v109, v109 quad_perm:[2,3,0,1] row_mask:0xf bank_mask:0xf
	v_add_f32_dpp v110, v110, v110 quad_perm:[2,3,0,1] row_mask:0xf bank_mask:0xf
	v_add_f32_dpp v111, v111, v111 quad_perm:[2,3,0,1] row_mask:0xf bank_mask:0xf
	v_add_f32_dpp v112, v112, v112 quad_perm:[2,3,0,1] row_mask:0xf bank_mask:0xf
	v_add_f32_dpp v113, v113, v113 quad_perm:[2,3,0,1] row_mask:0xf bank_mask:0xf
	v_add_f32_dpp v114, v114, v114 quad_perm:[2,3,0,1] row_mask:0xf bank_mask:0xf
	v_add_f32_dpp v115, v115, v115 quad_perm:[2,3,0,1] row_mask:0xf bank_mask:0xf
	v_add_f32_dpp v108, v108, v108 row_half_mirror row_mask:0xf bank_mask:0xf
	v_add_f32_dpp v109, v109, v109 row_half_mirror row_mask:0xf bank_mask:0xf
	v_add_f32_dpp v110, v110, v110 row_half_mirror row_mask:0xf bank_mask:0xf
	v_add_f32_dpp v111, v111, v111 row_half_mirror row_mask:0xf bank_mask:0xf
	v_add_f32_dpp v112, v112, v112 row_half_mirror row_mask:0xf bank_mask:0xf
	v_add_f32_dpp v113, v113, v113 row_half_mirror row_mask:0xf bank_mask:0xf
	v_add_f32_dpp v114, v114, v114 row_half_mirror row_mask:0xf bank_mask:0xf
	v_add_f32_dpp v115, v115, v115 row_half_mirror row_mask:0xf bank_mask:0xf
	v_mov_b32_e32 v122, v108
	v_cmp_eq_u32_e64 s[0:1], 1, v5
	s_nop 1
	v_cndmask_b32_e64 v122, v122, v109, s[0:1]
	v_cmp_eq_u32_e64 s[0:1], 2, v5
	s_nop 1
	v_cndmask_b32_e64 v122, v122, v110, s[0:1]
	v_cmp_eq_u32_e64 s[0:1], 3, v5
	s_nop 1
	v_cndmask_b32_e64 v122, v122, v111, s[0:1]
	v_cmp_eq_u32_e64 s[0:1], 4, v5
	s_nop 1
	v_cndmask_b32_e64 v122, v122, v112, s[0:1]
	v_cmp_eq_u32_e64 s[0:1], 5, v5
	s_nop 1
	v_cndmask_b32_e64 v122, v122, v113, s[0:1]
	v_cmp_eq_u32_e64 s[0:1], 6, v5
	s_nop 1
	v_cndmask_b32_e64 v122, v122, v114, s[0:1]
	v_cmp_eq_u32_e64 s[0:1], 7, v5
	s_nop 1
	v_cndmask_b32_e64 v122, v122, v115, s[0:1]
	s_waitcnt vmcnt(11)
	v_cvt_pk_f32_fp8_e32 v[118:119], v76
	v_cvt_pk_f32_fp8_sdwa v[120:121], v76 src0_sel:WORD_1
	s_nop 0
	v_pk_mul_f32 v[116:117], v[118:119], v[28:29]
	v_cvt_pk_f32_fp8_e32 v[118:119], v77
	v_pk_fma_f32 v[116:117], v[120:121], v[30:31], v[116:117]
	v_cvt_pk_f32_fp8_sdwa v[120:121], v77 src0_sel:WORD_1
	v_pk_fma_f32 v[116:117], v[118:119], v[32:33], v[116:117]
	v_cvt_pk_f32_fp8_e32 v[118:119], v78
	v_pk_fma_f32 v[116:117], v[120:121], v[34:35], v[116:117]
	v_cvt_pk_f32_fp8_sdwa v[120:121], v78 src0_sel:WORD_1
	v_pk_fma_f32 v[116:117], v[118:119], v[36:37], v[116:117]
	v_cvt_pk_f32_fp8_e32 v[118:119], v79
	v_pk_fma_f32 v[116:117], v[120:121], v[38:39], v[116:117]
	v_cvt_pk_f32_fp8_sdwa v[120:121], v79 src0_sel:WORD_1
	v_pk_fma_f32 v[116:117], v[118:119], v[40:41], v[116:117]
	s_nop 0
	v_pk_fma_f32 v[116:117], v[120:121], v[42:43], v[116:117]
	v_add_f32_e32 v108, v116, v117
	s_waitcnt vmcnt(10)
	v_cvt_pk_f32_fp8_e32 v[118:119], v80
	v_cvt_pk_f32_fp8_sdwa v[120:121], v80 src0_sel:WORD_1
	s_nop 0
	v_pk_mul_f32 v[116:117], v[118:119], v[28:29]
	v_cvt_pk_f32_fp8_e32 v[118:119], v81
	v_pk_fma_f32 v[116:117], v[120:121], v[30:31], v[116:117]
	v_cvt_pk_f32_fp8_sdwa v[120:121], v81 src0_sel:WORD_1
	v_pk_fma_f32 v[116:117], v[118:119], v[32:33], v[116:117]
	v_cvt_pk_f32_fp8_e32 v[118:119], v82
	v_pk_fma_f32 v[116:117], v[120:121], v[34:35], v[116:117]
	v_cvt_pk_f32_fp8_sdwa v[120:121], v82 src0_sel:WORD_1
	v_pk_fma_f32 v[116:117], v[118:119], v[36:37], v[116:117]
	v_cvt_pk_f32_fp8_e32 v[118:119], v83
	v_pk_fma_f32 v[116:117], v[120:121], v[38:39], v[116:117]
	v_cvt_pk_f32_fp8_sdwa v[120:121], v83 src0_sel:WORD_1
	v_pk_fma_f32 v[116:117], v[118:119], v[40:41], v[116:117]
	s_nop 0
	v_pk_fma_f32 v[116:117], v[120:121], v[42:43], v[116:117]
	v_add_f32_e32 v109, v116, v117
	s_waitcnt vmcnt(9)
	v_cvt_pk_f32_fp8_e32 v[118:119], v84
	v_cvt_pk_f32_fp8_sdwa v[120:121], v84 src0_sel:WORD_1
	s_nop 0
	v_pk_mul_f32 v[116:117], v[118:119], v[28:29]
	v_cvt_pk_f32_fp8_e32 v[118:119], v85
	v_pk_fma_f32 v[116:117], v[120:121], v[30:31], v[116:117]
	v_cvt_pk_f32_fp8_sdwa v[120:121], v85 src0_sel:WORD_1
	v_pk_fma_f32 v[116:117], v[118:119], v[32:33], v[116:117]
	v_cvt_pk_f32_fp8_e32 v[118:119], v86
	v_pk_fma_f32 v[116:117], v[120:121], v[34:35], v[116:117]
	v_cvt_pk_f32_fp8_sdwa v[120:121], v86 src0_sel:WORD_1
	v_pk_fma_f32 v[116:117], v[118:119], v[36:37], v[116:117]
	v_cvt_pk_f32_fp8_e32 v[118:119], v87
	v_pk_fma_f32 v[116:117], v[120:121], v[38:39], v[116:117]
	v_cvt_pk_f32_fp8_sdwa v[120:121], v87 src0_sel:WORD_1
	v_pk_fma_f32 v[116:117], v[118:119], v[40:41], v[116:117]
	s_nop 0
	v_pk_fma_f32 v[116:117], v[120:121], v[42:43], v[116:117]
	v_add_f32_e32 v110, v116, v117
	s_waitcnt vmcnt(8)
	v_cvt_pk_f32_fp8_e32 v[118:119], v88
	v_cvt_pk_f32_fp8_sdwa v[120:121], v88 src0_sel:WORD_1
	s_nop 0
	v_pk_mul_f32 v[116:117], v[118:119], v[28:29]
	v_cvt_pk_f32_fp8_e32 v[118:119], v89
	v_pk_fma_f32 v[116:117], v[120:121], v[30:31], v[116:117]
	v_cvt_pk_f32_fp8_sdwa v[120:121], v89 src0_sel:WORD_1
	v_pk_fma_f32 v[116:117], v[118:119], v[32:33], v[116:117]
	v_cvt_pk_f32_fp8_e32 v[118:119], v90
	v_pk_fma_f32 v[116:117], v[120:121], v[34:35], v[116:117]
	v_cvt_pk_f32_fp8_sdwa v[120:121], v90 src0_sel:WORD_1
	v_pk_fma_f32 v[116:117], v[118:119], v[36:37], v[116:117]
	v_cvt_pk_f32_fp8_e32 v[118:119], v91
	v_pk_fma_f32 v[116:117], v[120:121], v[38:39], v[116:117]
	v_cvt_pk_f32_fp8_sdwa v[120:121], v91 src0_sel:WORD_1
	v_pk_fma_f32 v[116:117], v[118:119], v[40:41], v[116:117]
	s_nop 0
	v_pk_fma_f32 v[116:117], v[120:121], v[42:43], v[116:117]
	v_add_f32_e32 v111, v116, v117
	s_waitcnt vmcnt(7)
	v_cvt_pk_f32_fp8_e32 v[118:119], v92
	v_cvt_pk_f32_fp8_sdwa v[120:121], v92 src0_sel:WORD_1
	s_nop 0
	v_pk_mul_f32 v[116:117], v[118:119], v[28:29]
	v_cvt_pk_f32_fp8_e32 v[118:119], v93
	v_pk_fma_f32 v[116:117], v[120:121], v[30:31], v[116:117]
	v_cvt_pk_f32_fp8_sdwa v[120:121], v93 src0_sel:WORD_1
	v_pk_fma_f32 v[116:117], v[118:119], v[32:33], v[116:117]
	v_cvt_pk_f32_fp8_e32 v[118:119], v94
	v_pk_fma_f32 v[116:117], v[120:121], v[34:35], v[116:117]
	v_cvt_pk_f32_fp8_sdwa v[120:121], v94 src0_sel:WORD_1
	v_pk_fma_f32 v[116:117], v[118:119], v[36:37], v[116:117]
	v_cvt_pk_f32_fp8_e32 v[118:119], v95
	v_pk_fma_f32 v[116:117], v[120:121], v[38:39], v[116:117]
	v_cvt_pk_f32_fp8_sdwa v[120:121], v95 src0_sel:WORD_1
	v_pk_fma_f32 v[116:117], v[118:119], v[40:41], v[116:117]
	s_nop 0
	v_pk_fma_f32 v[116:117], v[120:121], v[42:43], v[116:117]
	v_add_f32_e32 v112, v116, v117
	s_waitcnt vmcnt(6)
	v_cvt_pk_f32_fp8_e32 v[118:119], v96
	v_cvt_pk_f32_fp8_sdwa v[120:121], v96 src0_sel:WORD_1
	s_nop 0
	v_pk_mul_f32 v[116:117], v[118:119], v[28:29]
	v_cvt_pk_f32_fp8_e32 v[118:119], v97
	v_pk_fma_f32 v[116:117], v[120:121], v[30:31], v[116:117]
	v_cvt_pk_f32_fp8_sdwa v[120:121], v97 src0_sel:WORD_1
	v_pk_fma_f32 v[116:117], v[118:119], v[32:33], v[116:117]
	v_cvt_pk_f32_fp8_e32 v[118:119], v98
	v_pk_fma_f32 v[116:117], v[120:121], v[34:35], v[116:117]
	v_cvt_pk_f32_fp8_sdwa v[120:121], v98 src0_sel:WORD_1
	v_pk_fma_f32 v[116:117], v[118:119], v[36:37], v[116:117]
	v_cvt_pk_f32_fp8_e32 v[118:119], v99
	v_pk_fma_f32 v[116:117], v[120:121], v[38:39], v[116:117]
	v_cvt_pk_f32_fp8_sdwa v[120:121], v99 src0_sel:WORD_1
	v_pk_fma_f32 v[116:117], v[118:119], v[40:41], v[116:117]
	s_nop 0
	v_pk_fma_f32 v[116:117], v[120:121], v[42:43], v[116:117]
	v_add_f32_e32 v113, v116, v117
	s_waitcnt vmcnt(5)
	v_cvt_pk_f32_fp8_e32 v[118:119], v100
	v_cvt_pk_f32_fp8_sdwa v[120:121], v100 src0_sel:WORD_1
	s_nop 0
	v_pk_mul_f32 v[116:117], v[118:119], v[28:29]
	v_cvt_pk_f32_fp8_e32 v[118:119], v101
	v_pk_fma_f32 v[116:117], v[120:121], v[30:31], v[116:117]
	v_cvt_pk_f32_fp8_sdwa v[120:121], v101 src0_sel:WORD_1
	v_pk_fma_f32 v[116:117], v[118:119], v[32:33], v[116:117]
	v_cvt_pk_f32_fp8_e32 v[118:119], v102
	v_pk_fma_f32 v[116:117], v[120:121], v[34:35], v[116:117]
	v_cvt_pk_f32_fp8_sdwa v[120:121], v102 src0_sel:WORD_1
	v_pk_fma_f32 v[116:117], v[118:119], v[36:37], v[116:117]
	v_cvt_pk_f32_fp8_e32 v[118:119], v103
	v_pk_fma_f32 v[116:117], v[120:121], v[38:39], v[116:117]
	v_cvt_pk_f32_fp8_sdwa v[120:121], v103 src0_sel:WORD_1
	v_pk_fma_f32 v[116:117], v[118:119], v[40:41], v[116:117]
	s_nop 0
	v_pk_fma_f32 v[116:117], v[120:121], v[42:43], v[116:117]
	v_add_f32_e32 v114, v116, v117
	s_waitcnt vmcnt(4)
	v_cvt_pk_f32_fp8_e32 v[118:119], v104
	v_cvt_pk_f32_fp8_sdwa v[120:121], v104 src0_sel:WORD_1
	s_nop 0
	v_pk_mul_f32 v[116:117], v[118:119], v[28:29]
	v_cvt_pk_f32_fp8_e32 v[118:119], v105
	v_pk_fma_f32 v[116:117], v[120:121], v[30:31], v[116:117]
	v_cvt_pk_f32_fp8_sdwa v[120:121], v105 src0_sel:WORD_1
	v_pk_fma_f32 v[116:117], v[118:119], v[32:33], v[116:117]
	v_cvt_pk_f32_fp8_e32 v[118:119], v106
	v_pk_fma_f32 v[116:117], v[120:121], v[34:35], v[116:117]
	v_cvt_pk_f32_fp8_sdwa v[120:121], v106 src0_sel:WORD_1
	v_pk_fma_f32 v[116:117], v[118:119], v[36:37], v[116:117]
	v_cvt_pk_f32_fp8_e32 v[118:119], v107
	v_pk_fma_f32 v[116:117], v[120:121], v[38:39], v[116:117]
	v_cvt_pk_f32_fp8_sdwa v[120:121], v107 src0_sel:WORD_1
	v_pk_fma_f32 v[116:117], v[118:119], v[40:41], v[116:117]
	s_nop 0
	v_pk_fma_f32 v[116:117], v[120:121], v[42:43], v[116:117]
	v_add_f32_e32 v115, v116, v117
	v_add_f32_dpp v108, v108, v108 quad_perm:[1,0,3,2] row_mask:0xf bank_mask:0xf
	v_add_f32_dpp v109, v109, v109 quad_perm:[1,0,3,2] row_mask:0xf bank_mask:0xf
	v_add_f32_dpp v110, v110, v110 quad_perm:[1,0,3,2] row_mask:0xf bank_mask:0xf
	v_add_f32_dpp v111, v111, v111 quad_perm:[1,0,3,2] row_mask:0xf bank_mask:0xf
	v_add_f32_dpp v112, v112, v112 quad_perm:[1,0,3,2] row_mask:0xf bank_mask:0xf
	v_add_f32_dpp v113, v113, v113 quad_perm:[1,0,3,2] row_mask:0xf bank_mask:0xf
	v_add_f32_dpp v114, v114, v114 quad_perm:[1,0,3,2] row_mask:0xf bank_mask:0xf
	v_add_f32_dpp v115, v115, v115 quad_perm:[1,0,3,2] row_mask:0xf bank_mask:0xf
	v_add_f32_dpp v108, v108, v108 quad_perm:[2,3,0,1] row_mask:0xf bank_mask:0xf
	v_add_f32_dpp v109, v109, v109 quad_perm:[2,3,0,1] row_mask:0xf bank_mask:0xf
	v_add_f32_dpp v110, v110, v110 quad_perm:[2,3,0,1] row_mask:0xf bank_mask:0xf
	v_add_f32_dpp v111, v111, v111 quad_perm:[2,3,0,1] row_mask:0xf bank_mask:0xf
	v_add_f32_dpp v112, v112, v112 quad_perm:[2,3,0,1] row_mask:0xf bank_mask:0xf
	v_add_f32_dpp v113, v113, v113 quad_perm:[2,3,0,1] row_mask:0xf bank_mask:0xf
	v_add_f32_dpp v114, v114, v114 quad_perm:[2,3,0,1] row_mask:0xf bank_mask:0xf
	v_add_f32_dpp v115, v115, v115 quad_perm:[2,3,0,1] row_mask:0xf bank_mask:0xf
	v_add_f32_dpp v108, v108, v108 row_half_mirror row_mask:0xf bank_mask:0xf
	v_add_f32_dpp v109, v109, v109 row_half_mirror row_mask:0xf bank_mask:0xf
	v_add_f32_dpp v110, v110, v110 row_half_mirror row_mask:0xf bank_mask:0xf
	v_add_f32_dpp v111, v111, v111 row_half_mirror row_mask:0xf bank_mask:0xf
	v_add_f32_dpp v112, v112, v112 row_half_mirror row_mask:0xf bank_mask:0xf
	v_add_f32_dpp v113, v113, v113 row_half_mirror row_mask:0xf bank_mask:0xf
	v_add_f32_dpp v114, v114, v114 row_half_mirror row_mask:0xf bank_mask:0xf
	v_add_f32_dpp v115, v115, v115 row_half_mirror row_mask:0xf bank_mask:0xf
	v_mov_b32_e32 v123, v108
	v_cmp_eq_u32_e64 s[0:1], 1, v5
	s_nop 1
	v_cndmask_b32_e64 v123, v123, v109, s[0:1]
	v_cmp_eq_u32_e64 s[0:1], 2, v5
	s_nop 1
	v_cndmask_b32_e64 v123, v123, v110, s[0:1]
	v_cmp_eq_u32_e64 s[0:1], 3, v5
	s_nop 1
	v_cndmask_b32_e64 v123, v123, v111, s[0:1]
	v_cmp_eq_u32_e64 s[0:1], 4, v5
	s_nop 1
	v_cndmask_b32_e64 v123, v123, v112, s[0:1]
	v_cmp_eq_u32_e64 s[0:1], 5, v5
	s_nop 1
	v_cndmask_b32_e64 v123, v123, v113, s[0:1]
	v_cmp_eq_u32_e64 s[0:1], 6, v5
	s_nop 1
	v_cndmask_b32_e64 v123, v123, v114, s[0:1]
	v_cmp_eq_u32_e64 s[0:1], 7, v5
	s_nop 1
	v_cndmask_b32_e64 v123, v123, v115, s[0:1]
	s_lshl_b32 s0, s38, 9
	v_add_u32_e32 v124, s0, v3
	global_store_dword v124, v122, s[46:47]
	global_store_dword v124, v123, s[46:47] offset:256
	s_add_i32 s38, s38, s39
	s_branch .Lpu_tok
.Lpu_part_next:
	s_add_i32 s40, s40, s41
	s_branch .Lpu_part
.Lpu_done:
	s_waitcnt vmcnt(0)
	s_branch .LBB0_74
.Lpu_fin:
	v_lshlrev_b32_e32 v6, 2, v167
	v_readlane_b32 s0, v250, 0
	v_readlane_b32 s1, v250, 1
	v_readfirstlane_b32 s20, v135
	s_nop 3
	s_lshr_b32 s20, s20, 6
	s_lshl_b32 s38, s0, 3
	s_add_i32 s38, s38, s20
	s_lshl_b32 s39, s1, 3
	s_add_u32 s42, s66, 0x20b6c000
	s_addc_u32 s43, s67, 0
	s_add_u32 s44, s66, 0x22b6c000
	s_addc_u32 s45, s67, 0
	s_add_u32 s46, s66, 0x25f6c000
	s_addc_u32 s47, s67, 0
	s_add_u32 s48, s66, 0x670c000
	s_addc_u32 s49, s67, 0
	s_add_u32 s50, s66, 0x671c000
	s_addc_u32 s51, s67, 0
.Lpf_tok:
	s_cmp_gt_u32 s38, 0xffff
	s_cbranch_scc1 .Lpf_done
	s_lshl_b32 s0, s38, 9
	v_add_u32_e32 v0, s0, v6
	global_load_dword v16, v0, s[42:43]
	global_load_dword v17, v0, s[44:45]
	global_load_dword v8, v0, s[46:47]
	v_add_u32_e32 v1, 0x2000000, v0
	global_load_dword v9, v1, s[46:47]
	v_add_u32_e32 v1, 0x4000000, v0
	global_load_dword v10, v1, s[46:47]
	v_add_u32_e32 v1, 0x6000000, v0
	global_load_dword v11, v1, s[46:47]
	v_add_u32_e32 v1, 0x8000000, v0
	global_load_dword v12, v1, s[46:47]
	v_add_u32_e32 v1, 0xa000000, v0
	global_load_dword v13, v1, s[46:47]
	v_add_u32_e32 v1, 0xc000000, v0
	global_load_dword v14, v1, s[46:47]
	v_add_u32_e32 v1, 0xe000000, v0
	global_load_dword v15, v1, s[46:47]
	global_load_dword v32, v0, s[42:43] offset:256
	global_load_dword v33, v0, s[44:45] offset:256
	global_load_dword v24, v0, s[46:47] offset:256
	v_add_u32_e32 v1, 0x2000000, v0
	global_load_dword v25, v1, s[46:47] offset:256
	v_add_u32_e32 v1, 0x4000000, v0
	global_load_dword v26, v1, s[46:47] offset:256
	v_add_u32_e32 v1, 0x6000000, v0
	global_load_dword v27, v1, s[46:47] offset:256
	v_add_u32_e32 v1, 0x8000000, v0
	global_load_dword v28, v1, s[46:47] offset:256
	v_add_u32_e32 v1, 0xa000000, v0
	global_load_dword v29, v1, s[46:47] offset:256
	v_add_u32_e32 v1, 0xc000000, v0
	global_load_dword v30, v1, s[46:47] offset:256
	v_add_u32_e32 v1, 0xe000000, v0
	global_load_dword v31, v1, s[46:47] offset:256
	s_waitcnt vmcnt(0)
	v_lshlrev_b32_e32 v2, 2, v16
	global_load_dword v18, v2, s[48:49]
	global_load_dword v19, v2, s[50:51]
	v_lshlrev_b32_e32 v3, 2, v32
	global_load_dword v34, v3, s[48:49]
	global_load_dword v35, v3, s[50:51]
	s_waitcnt vmcnt(0)
	v_add_f32_e32 v40, v8, v9
	v_add_f32_e32 v40, v40, v10
	v_add_f32_e32 v40, v40, v11
	v_add_f32_e32 v40, v40, v12
	v_add_f32_e32 v40, v40, v13
	v_add_f32_e32 v40, v40, v14
	v_add_f32_e32 v40, v40, v15
	v_mul_f32_e32 v41, v40, v18
	v_mul_f32_e32 v44, v17, v19
	v_mul_f32_e32 v42, 0x3f3504f3, v41
	v_cmp_nlt_f32_e64 s[20:21], |v42|, 1.0
	s_and_saveexec_b64 s[0:1], s[20:21]
	s_xor_b64 s[0:1], exec, s[0:1]
	s_cbranch_execz .Lpf_e0a
	v_fma_f32 v43, |v42|, s36, v181
	v_fma_f32 v43, |v42|, v43, s37
	v_fma_f32 v43, |v42|, v43, s27
	v_fma_f32 v43, |v42|, v43, s29
	v_fma_f32 v43, |v42|, v43, s22
	v_fma_f32 v43, |v42|, v43, s23
	v_fma_f32 v43, |v42|, v43, |v42|
	v_mul_f32_e32 v45, 0xbfb8aa3b, v43
	v_fma_f32 v46, v43, s96, -v45
	v_rndne_f32_e32 v47, v45
	v_fmac_f32_e32 v46, 0xb2a5705f, v43
	v_sub_f32_e32 v45, v45, v47
	v_add_f32_e32 v45, v45, v46
	v_cvt_i32_f32_e32 v46, v47
	v_exp_f32_e32 v45, v45
	v_cmp_nlt_f32_e64 s[20:21], s2, v43
	v_ldexp_f32 v45, v45, v46
	s_nop 0
	v_cndmask_b32_e64 v45, 0, v45, s[20:21]
	v_cmp_ngt_f32_e64 s[20:21], s3, v43
	s_nop 1
	v_cndmask_b32_e64 v43, v182, v45, s[20:21]
	v_sub_f32_e32 v43, 1.0, v43
.Lpf_e0a:
	s_andn2_saveexec_b64 s[0:1], s[0:1]
	v_mul_f32_e32 v43, v42, v42
	v_fmamk_f32 v45, v43, 0xba1345e1, v164
	v_fmaak_f32 v45, v43, v45, 0xbcdac9b8
	v_fmaak_f32 v45, v43, v45, 0x3de703be
	v_fmaak_f32 v45, v43, v45, 0xbec09330
	v_fmaak_f32 v43, v43, v45, 0x3e0375d0
	v_fma_f32 v43, |v42|, v43, |v42|
	s_or_b64 exec, exec, s[0:1]
	v_mul_f32_e32 v44, 0.5, v44
	v_mul_f32_e32 v44, v41, v44
	v_bfi_b32 v45, s26, v43, v42
	v_add_f32_e32 v45, 1.0, v45
	v_mul_f32_e32 v50, v44, v45
	v_add_f32_e32 v40, v24, v25
	v_add_f32_e32 v40, v40, v26
	v_add_f32_e32 v40, v40, v27
	v_add_f32_e32 v40, v40, v28
	v_add_f32_e32 v40, v40, v29
	v_add_f32_e32 v40, v40, v30
	v_add_f32_e32 v40, v40, v31
	v_mul_f32_e32 v41, v40, v34
	v_mul_f32_e32 v44, v33, v35
	v_mul_f32_e32 v42, 0x3f3504f3, v41
	v_cmp_nlt_f32_e64 s[20:21], |v42|, 1.0
	s_and_saveexec_b64 s[0:1], s[20:21]
	s_xor_b64 s[0:1], exec, s[0:1]
	s_cbranch_execz .Lpf_e1a
	v_fma_f32 v43, |v42|, s36, v181
	v_fma_f32 v43, |v42|, v43, s37
	v_fma_f32 v43, |v42|, v43, s27
	v_fma_f32 v43, |v42|, v43, s29
	v_fma_f32 v43, |v42|, v43, s22
	v_fma_f32 v43, |v42|, v43, s23
	v_fma_f32 v43, |v42|, v43, |v42|
	v_mul_f32_e32 v45, 0xbfb8aa3b, v43
	v_fma_f32 v46, v43, s96, -v45
	v_rndne_f32_e32 v47, v45
	v_fmac_f32_e32 v46, 0xb2a5705f, v43
	v_sub_f32_e32 v45, v45, v47
	v_add_f32_e32 v45, v45, v46
	v_cvt_i32_f32_e32 v46, v47
	v_exp_f32_e32 v45, v45
	v_cmp_nlt_f32_e64 s[20:21], s2, v43
	v_ldexp_f32 v45, v45, v46
	s_nop 0
	v_cndmask_b32_e64 v45, 0, v45, s[20:21]
	v_cmp_ngt_f32_e64 s[20:21], s3, v43
	s_nop 1
	v_cndmask_b32_e64 v43, v182, v45, s[20:21]
	v_sub_f32_e32 v43, 1.0, v43
.Lpf_e1a:
	s_andn2_saveexec_b64 s[0:1], s[0:1]
	v_mul_f32_e32 v43, v42, v42
	v_fmamk_f32 v45, v43, 0xba1345e1, v164
	v_fmaak_f32 v45, v43, v45, 0xbcdac9b8
	v_fmaak_f32 v45, v43, v45, 0x3de703be
	v_fmaak_f32 v45, v43, v45, 0xbec09330
	v_fmaak_f32 v43, v43, v45, 0x3e0375d0
	v_fma_f32 v43, |v42|, v43, |v42|
	s_or_b64 exec, exec, s[0:1]
	v_mul_f32_e32 v44, 0.5, v44
	v_mul_f32_e32 v44, v41, v44
	v_bfi_b32 v45, s26, v43, v42
	v_add_f32_e32 v45, 1.0, v45
	v_mul_f32_e32 v51, v44, v45
	global_store_dword v0, v50, s[46:47]
	global_store_dword v0, v51, s[46:47] offset:256
	s_add_i32 s38, s38, s39
	s_branch .Lpf_tok

.Lpv_orig:
	v_mov_b32_e32 v14, v135
	v_readlane_b32 s0, v250, 0
	s_nop 0
	v_readlane_b32 s0, v250, 1
	v_readlane_b32 s1, v250, 2
	s_mov_b64 s[0:1], 0
	s_add_u32 s34, s66, s0
	s_addc_u32 s35, s67, s1
	s_add_i32 s0, 0, 0x26c08
	s_cmp_lg_u32 s0, -1
	s_cselect_b32 s20, s0, 0
	s_mov_b64 s[0:1], src_shared_base
	s_cselect_b32 s0, s1, 0
	v_mov_b32_e32 v1, s0
	s_add_i32 s0, 0, 0x26c0c
	s_cmp_lg_u32 s0, -1
	v_mov_b32_e32 v0, s20
	s_cselect_b32 s0, s0, 0
	s_cselect_b32 s1, s1, 0
	flat_load_dword v3, v[0:1] sc0 sc1
	s_waitcnt vmcnt(0)
	v_mov_b32_e32 v0, s0
	v_mov_b32_e32 v1, s1
	flat_load_dword v2, v[0:1] sc0 sc1
	s_waitcnt vmcnt(0)
	global_load_dword v4, v163, s[34:35] offset:2048 sc1
	global_load_dword v5, v163, s[34:35] offset:2052 sc1
	global_load_dword v6, v163, s[34:35] offset:2056 sc1
	s_waitcnt lgkmcnt(0)
	v_cmp_eq_u32_e64 s[38:39], 1, v3
	s_waitcnt vmcnt(2)
	v_cmp_ne_u32_e32 vcc, 0, v4
	s_nop 1
	v_cndmask_b32_e64 v0, 0, 1, vcc
	s_waitcnt vmcnt(1)
	v_cmp_ne_u32_e64 s[40:41], 0, v5
	s_and_b64 s[38:39], s[40:41], s[38:39]
	s_waitcnt vmcnt(0)
	v_cmp_ne_u32_e64 s[42:43], 0, v6
	v_cndmask_b32_e64 v7, 0, 1, s[40:41]
	v_addc_co_u32_e64 v8, s[40:41], 0, v0, s[40:41]
	v_cmp_eq_u32_e64 s[40:41], 2, v3
	v_cndmask_b32_e64 v1, 0, v0, s[38:39]
	s_and_b64 s[40:41], s[42:43], s[40:41]
	v_cndmask_b32_e64 v9, 0, 1, s[42:43]
	v_addc_co_u32_e64 v0, s[42:43], v7, v0, s[42:43]
	global_load_dword v7, v163, s[34:35] offset:2060 sc1
	v_cmp_eq_u32_e64 s[42:43], 3, v3
	v_cndmask_b32_e64 v1, v1, v8, s[40:41]
	s_waitcnt vmcnt(0)
	v_cmp_ne_u32_e64 s[44:45], 0, v7
	s_and_b64 s[42:43], s[44:45], s[42:43]
	s_nop 0
	v_cndmask_b32_e64 v10, 0, 1, s[44:45]
	v_addc_co_u32_e64 v11, s[44:45], v8, v9, s[44:45]
	global_load_dword v8, v163, s[34:35] offset:2064 sc1
	global_load_dword v9, v163, s[34:35] offset:2068 sc1
	v_cmp_eq_u32_e64 s[44:45], 4, v3
	v_cndmask_b32_e64 v1, v1, v0, s[42:43]
	s_waitcnt vmcnt(1)
	v_cmp_ne_u32_e64 s[46:47], 0, v8
	s_and_b64 s[44:45], s[46:47], s[44:45]
	s_nop 0
	v_cndmask_b32_e64 v12, 0, 1, s[46:47]
	v_addc_co_u32_e64 v0, s[46:47], v0, v10, s[46:47]
	global_load_dword v10, v163, s[34:35] offset:2072 sc1
	s_waitcnt vmcnt(1)
	v_cmp_ne_u32_e64 s[48:49], 0, v9
	v_cmp_eq_u32_e64 s[46:47], 5, v3
	v_cndmask_b32_e64 v1, v1, v11, s[44:45]
	s_and_b64 s[46:47], s[48:49], s[46:47]
	v_cndmask_b32_e64 v13, 0, 1, s[48:49]
	v_addc_co_u32_e64 v12, s[48:49], v11, v12, s[48:49]
	global_load_dword v11, v163, s[34:35] offset:2076 sc1
	v_cmp_eq_u32_e64 s[48:49], 6, v3
	v_cndmask_b32_e64 v1, v1, v0, s[46:47]
	s_waitcnt vmcnt(1)
	v_cmp_ne_u32_e64 s[50:51], 0, v10
	s_and_b64 s[48:49], s[50:51], s[48:49]
	s_nop 0
	v_cndmask_b32_e64 v15, 0, 1, s[50:51]
	v_addc_co_u32_e64 v0, s[50:51], v0, v13, s[50:51]
	v_cmp_eq_u32_e64 s[50:51], 7, v3
	v_cndmask_b32_e64 v1, v1, v12, s[48:49]
	s_waitcnt vmcnt(0)
	v_cmp_ne_u32_e64 s[52:53], 0, v11
	s_and_b64 s[50:51], s[52:53], s[50:51]
	s_nop 0
	v_cndmask_b32_e64 v13, 0, 1, s[52:53]
	v_addc_co_u32_e64 v15, s[52:53], v12, v15, s[52:53]
	global_load_dword v12, v163, s[34:35] offset:2080 sc1
	v_cmp_eq_u32_e64 s[52:53], 8, v3
	v_cndmask_b32_e64 v1, v1, v0, s[50:51]
	s_waitcnt vmcnt(0)
	v_cmp_ne_u32_e64 s[54:55], 0, v12
	s_and_b64 s[52:53], s[54:55], s[52:53]
	s_nop 0
	v_cndmask_b32_e64 v16, 0, 1, s[54:55]
	v_addc_co_u32_e64 v0, s[54:55], v0, v13, s[54:55]
	global_load_dword v13, v163, s[34:35] offset:2084 sc1
	v_cmp_eq_u32_e64 s[54:55], 9, v3
	v_cndmask_b32_e64 v1, v1, v15, s[52:53]
	s_waitcnt vmcnt(0)
	v_cmp_ne_u32_e64 s[56:57], 0, v13
	s_and_b64 s[54:55], s[56:57], s[54:55]
	s_nop 0
	v_cndmask_b32_e64 v17, 0, 1, s[56:57]
	v_addc_co_u32_e64 v18, s[56:57], v15, v16, s[56:57]
	global_load_dword v15, v163, s[34:35] offset:2088 sc1
	global_load_dword v16, v163, s[34:35] offset:2092 sc1
	v_cmp_eq_u32_e64 s[56:57], 10, v3
	v_cndmask_b32_e64 v1, v1, v0, s[54:55]
	s_waitcnt vmcnt(1)
	v_cmp_ne_u32_e64 s[58:59], 0, v15
	s_and_b64 s[56:57], s[58:59], s[56:57]
	s_nop 0
	v_cndmask_b32_e64 v19, 0, 1, s[58:59]
	v_addc_co_u32_e64 v0, s[58:59], v0, v17, s[58:59]
	global_load_dword v17, v163, s[34:35] offset:2096 sc1
	s_waitcnt vmcnt(1)
	v_cmp_ne_u32_e64 s[60:61], 0, v16
	v_cmp_eq_u32_e64 s[58:59], 11, v3
	v_cndmask_b32_e64 v1, v1, v18, s[56:57]
	s_and_b64 s[58:59], s[60:61], s[58:59]
	v_cndmask_b32_e64 v20, 0, 1, s[60:61]
	v_addc_co_u32_e64 v19, s[60:61], v18, v19, s[60:61]
	global_load_dword v18, v163, s[34:35] offset:2100 sc1
	v_cmp_eq_u32_e64 s[60:61], 12, v3
	v_cndmask_b32_e64 v1, v1, v0, s[58:59]
	s_waitcnt vmcnt(1)
	v_cmp_ne_u32_e64 s[62:63], 0, v17
	s_and_b64 s[60:61], s[62:63], s[60:61]
	s_nop 0
	v_cndmask_b32_e64 v21, 0, 1, s[62:63]
	v_addc_co_u32_e64 v0, s[62:63], v0, v20, s[62:63]
	v_cmp_eq_u32_e64 s[62:63], 13, v3
	v_cndmask_b32_e64 v1, v1, v19, s[60:61]
	s_waitcnt vmcnt(0)
	v_cmp_ne_u32_e64 s[64:65], 0, v18
	s_and_b64 s[62:63], s[64:65], s[62:63]
	s_nop 0
	v_cndmask_b32_e64 v20, 0, 1, s[64:65]
	v_addc_co_u32_e64 v21, s[64:65], v19, v21, s[64:65]
	global_load_dword v19, v163, s[34:35] offset:2104 sc1
	v_cmp_eq_u32_e64 s[64:65], 14, v3
	v_cndmask_b32_e64 v1, v1, v0, s[62:63]
	s_waitcnt vmcnt(0)
	v_cmp_ne_u32_e64 s[66:67], 0, v19
	s_and_b64 s[64:65], s[66:67], s[64:65]
	v_cndmask_b32_e64 v1, v1, v21, s[64:65]
	v_addc_co_u32_e64 v21, s[66:67], v0, v20, s[66:67]
	global_load_dword v20, v163, s[34:35] offset:2108 sc1
	v_cmp_eq_u32_e64 s[66:67], 15, v3
	s_waitcnt vmcnt(0)
	v_cmp_ne_u32_e64 s[68:69], 0, v20
	s_and_b64 s[66:67], s[68:69], s[66:67]
	v_cndmask_b32_e64 v1, v1, v21, s[66:67]
	v_cmp_gt_u32_e64 s[70:71], 8, v1
	s_and_saveexec_b64 s[30:31], s[70:71]
	s_cbranch_execz .LBB0_73
	s_add_u32 s70, s34, 0x20b6c000
	s_addc_u32 s71, s35, 0
	v_cndmask_b32_e64 v22, 0, 1, s[68:69]
	s_add_u32 s72, s34, 0x25f6c000
	v_cmp_eq_u32_e64 s[68:69], 0, v3
	s_addc_u32 s73, s35, 0
	s_and_b64 vcc, vcc, s[68:69]
	v_cndmask_b32_e32 v3, 1, v4, vcc
	v_cndmask_b32_e64 v3, v3, v5, s[38:39]
	v_cndmask_b32_e64 v3, v3, v6, s[40:41]
	v_cndmask_b32_e64 v3, v3, v7, s[42:43]
	v_cndmask_b32_e64 v3, v3, v8, s[44:45]
	v_cndmask_b32_e64 v3, v3, v9, s[46:47]
	v_cndmask_b32_e64 v3, v3, v10, s[48:49]
	v_cndmask_b32_e64 v3, v3, v11, s[50:51]
	v_cndmask_b32_e64 v3, v3, v12, s[52:53]
	v_cndmask_b32_e64 v3, v3, v13, s[54:55]
	v_cndmask_b32_e64 v3, v3, v15, s[56:57]
	v_cndmask_b32_e64 v3, v3, v16, s[58:59]
	v_cndmask_b32_e64 v3, v3, v17, s[60:61]
	v_cndmask_b32_e64 v3, v3, v18, s[62:63]
	v_add_u32_e32 v40, v21, v22
	v_ashrrev_i32_e32 v21, 6, v14
	v_cndmask_b32_e64 v3, v3, v19, s[64:65]
	v_cndmask_b32_e64 v3, v3, v20, s[66:67]
	v_lshlrev_b32_e32 v5, 4, v14
	v_lshl_add_u32 v2, v2, 3, v21
	v_lshrrev_b32_e32 v4, 2, v14
	v_and_b32_e32 v132, 0x70, v5
	v_lshlrev_b32_e32 v42, 3, v3
	v_ashrrev_i32_e32 v3, 31, v2
	v_and_b32_e32 v0, 63, v14
	v_and_or_b32 v15, v4, 14, v132
	s_mov_b32 s0, 0x10000
	v_lshlrev_b64 v[8:9], 9, v[2:3]
	v_and_b32_e32 v3, 32, v14
	v_cmp_gt_i32_e64 s[38:39], s0, v2
	v_lshl_or_b32 v8, v0, 2, v8
	v_lshl_add_u64 v[12:13], s[34:35], 0, v[132:133]
	s_mov_b64 s[0:1], 0x4010000
	v_cmp_eq_u32_e64 s[40:41], 0, v3
	v_and_b32_e32 v3, 16, v14
	v_lshlrev_b32_e32 v132, 1, v15
	v_bfe_u32 v41, v14, 3, 3
	v_or_b32_e32 v10, 0x100, v8
	v_mov_b32_e32 v11, v9
	v_lshl_add_u64 v[12:13], v[12:13], 0, s[0:1]
	v_cmp_eq_u32_e64 s[42:43], 0, v3
	v_and_b32_e32 v3, 8, v14
	v_lshl_add_u64 v[14:15], s[34:35], 0, v[132:133]
	s_mov_b64 s[0:1], 0x10b6c000
	v_lshl_add_u64 v[4:5], s[70:71], 0, v[8:9]
	v_lshl_add_u64 v[6:7], s[70:71], 0, v[10:11]
	v_lshl_add_u64 v[8:9], s[72:73], 0, v[8:9]
	v_lshl_add_u64 v[10:11], s[72:73], 0, v[10:11]
	v_cmp_eq_u32_e64 s[44:45], 0, v3
	v_lshl_add_u64 v[14:15], v[14:15], 0, s[0:1]
	s_mov_b64 s[48:49], 0
	s_branch .LBB0_66

.LBB0_89:
	v_lshl_or_b32 v138, s62, 6, v200
	v_ashrrev_i32_e32 v139, 31, v138
	v_lshlrev_b64 v[0:1], 11, v[138:139]
	v_lshl_add_u64 v[0:1], v[72:73], 0, v[0:1]
	s_barrier
	s_mov_b64 s[34:35], 0
	s_branch .LBB0_78
	global_load_dwordx4 v[8:11], v[0:1], off offset:16
	global_load_dwordx4 v[12:15], v[0:1], off
	v_lshlrev_b64 v[0:1], 9, v[138:139]
	v_lshl_or_b32 v0, v68, 2, v0
	v_or_b32_e32 v4, 0x100, v0
	v_mov_b32_e32 v5, v1
	v_lshl_add_u64 v[6:7], s[54:55], 0, v[4:5]
	v_lshl_add_u64 v[4:5], s[56:57], 0, v[4:5]
	v_lshl_add_u64 v[2:3], s[54:55], 0, v[0:1]
	v_lshl_add_u64 v[0:1], s[56:57], 0, v[0:1]
	global_load_dword v16, v[4:5], off
	global_load_dword v17, v[0:1], off
	global_load_dword v140, v[2:3], off
	global_load_dword v142, v[6:7], off
	s_mov_b64 s[34:35], 0
	v_or_b32_e32 v127, 15, v138
	s_waitcnt vmcnt(5)
	v_mov_b64_e32 v[0:1], v[8:9]
	s_waitcnt vmcnt(4)
	v_mov_b64_e32 v[4:5], v[12:13]
	v_mov_b64_e32 v[2:3], v[10:11]
	v_mov_b64_e32 v[6:7], v[14:15]
	s_waitcnt vmcnt(3)
	v_mov_b32_e32 v145, v16
	s_waitcnt vmcnt(2)
	v_mov_b32_e32 v131, v17
	s_branch .LBB0_91

.LBB0_252:
	s_or_b64 exec, exec, s[94:95]
	v_cndmask_b32_e64 v32, 0, v32, s[40:41]
	v_cndmask_b32_e64 v33, 0, v33, s[42:43]
	v_add_f32_e32 v32, v32, v33
	s_waitcnt lgkmcnt(0)
	v_cndmask_b32_e64 v33, 0, v238, s[44:45]
	v_add_f32_e32 v32, v32, v33
	v_add_f32_e32 v33, v32, v237
	v_sub_f32_e32 v32, v33, v36
	v_mul_f32_e32 v32, 0x3fb8aa3b, v32
	v_exp_f32_e32 v237, v32
	ds_read_u16 v32, v202 offset:16384
	s_and_b64 vcc, exec, s[84:85]
	s_mov_b32 s24, 0x8000
	v_rcp_f32_e32 v238, v237
	s_movk_i32 s25, 0x1000
	s_waitcnt lgkmcnt(0)
	v_lshlrev_b32_e32 v32, 16, v32
	v_mul_f32_e32 v32, v238, v32
	v_cvt_pk_bf16_f32 v238, v32, s0
	ds_write_b16 v202, v238 offset:16384
	s_cbranch_vccnz .LBB0_254
	ds_read_u16 v238, v202
	s_waitcnt lgkmcnt(0)
	v_lshlrev_b32_e32 v238, 16, v238
	v_mul_f32_e32 v237, v237, v238
	v_cvt_pk_bf16_f32 v237, v237, s0
	ds_write_b16 v202, v237
.LBB0_254:
	v_add_f32_e32 v236, v33, v236
	v_sub_f32_e32 v33, v236, v36
	v_mul_f32_e32 v33, 0x3fb8aa3b, v33
	v_exp_f32_e32 v237, v33
	ds_read_u16 v33, v203 offset:16640
	s_and_b64 vcc, exec, s[84:85]
	v_rcp_f32_e32 v238, v237
	s_waitcnt lgkmcnt(0)
	v_lshlrev_b32_e32 v33, 16, v33
	v_mul_f32_e32 v33, v238, v33
	v_cvt_pk_bf16_f32 v238, v33, s0
	ds_write_b16 v203, v238 offset:16640
	s_cbranch_vccnz .LBB0_256
	ds_read_u16 v238, v203 offset:256
	s_waitcnt lgkmcnt(0)
	v_lshlrev_b32_e32 v238, 16, v238
	v_mul_f32_e32 v237, v237, v238
	v_cvt_pk_bf16_f32 v237, v237, s0
	ds_write_b16 v203, v237 offset:256
.LBB0_256:
	v_add_f32_e32 v236, v236, v132
	v_sub_f32_e32 v132, v236, v36
	v_mul_f32_e32 v132, 0x3fb8aa3b, v132
	v_exp_f32_e32 v237, v132
	ds_read_u16 v132, v204 offset:16896
	s_and_b64 vcc, exec, s[84:85]
	v_rcp_f32_e32 v238, v237
	s_waitcnt lgkmcnt(0)
	v_lshlrev_b32_e32 v132, 16, v132
	v_mul_f32_e32 v132, v238, v132
	v_cvt_pk_bf16_f32 v238, v132, s0
	ds_write_b16 v204, v238 offset:16896
	s_cbranch_vccnz .LBB0_258
	ds_read_u16 v238, v204 offset:512
	s_waitcnt lgkmcnt(0)
	v_lshlrev_b32_e32 v238, 16, v238
	v_mul_f32_e32 v237, v237, v238
	v_cvt_pk_bf16_f32 v237, v237, s0
	ds_write_b16 v204, v237 offset:512
.LBB0_258:
	v_add_f32_e32 v236, v236, v47
	v_sub_f32_e32 v47, v236, v36
	v_mul_f32_e32 v47, 0x3fb8aa3b, v47
	v_exp_f32_e32 v237, v47
	ds_read_u16 v47, v205 offset:17152
	s_and_b64 vcc, exec, s[84:85]
	v_rcp_f32_e32 v238, v237
	s_waitcnt lgkmcnt(0)
	v_lshlrev_b32_e32 v47, 16, v47
	v_mul_f32_e32 v47, v238, v47
	v_cvt_pk_bf16_f32 v238, v47, s0
	ds_write_b16 v205, v238 offset:17152
	s_cbranch_vccnz .LBB0_260
	ds_read_u16 v238, v205 offset:768
	s_waitcnt lgkmcnt(0)
	v_lshlrev_b32_e32 v238, 16, v238
	v_mul_f32_e32 v237, v237, v238
	v_cvt_pk_bf16_f32 v237, v237, s0
	ds_write_b16 v205, v237 offset:768
.LBB0_260:
	v_add_f32_e32 v236, v236, v46
	v_sub_f32_e32 v46, v236, v36
	v_mul_f32_e32 v46, 0x3fb8aa3b, v46
	v_exp_f32_e32 v237, v46
	ds_read_u16 v46, v206 offset:17408
	s_and_b64 vcc, exec, s[84:85]
	v_rcp_f32_e32 v238, v237
	s_waitcnt lgkmcnt(0)
	v_lshlrev_b32_e32 v46, 16, v46
	v_mul_f32_e32 v46, v238, v46
	v_cvt_pk_bf16_f32 v238, v46, s0
	ds_write_b16 v206, v238 offset:17408
	s_cbranch_vccnz .LBB0_262
	ds_read_u16 v238, v206 offset:1024
	s_waitcnt lgkmcnt(0)
	v_lshlrev_b32_e32 v238, 16, v238
	v_mul_f32_e32 v237, v237, v238
	v_cvt_pk_bf16_f32 v237, v237, s0
	ds_write_b16 v206, v237 offset:1024
.LBB0_262:
	v_add_f32_e32 v236, v236, v45
	v_sub_f32_e32 v45, v236, v36
	v_mul_f32_e32 v45, 0x3fb8aa3b, v45
	v_exp_f32_e32 v237, v45
	ds_read_u16 v45, v207 offset:17664
	s_and_b64 vcc, exec, s[84:85]
	v_rcp_f32_e32 v238, v237
	s_waitcnt lgkmcnt(0)
	v_lshlrev_b32_e32 v45, 16, v45
	v_mul_f32_e32 v45, v238, v45
	v_cvt_pk_bf16_f32 v238, v45, s0
	ds_write_b16 v207, v238 offset:17664
	s_cbranch_vccnz .LBB0_264
	ds_read_u16 v238, v207 offset:1280
	s_waitcnt lgkmcnt(0)
	v_lshlrev_b32_e32 v238, 16, v238
	v_mul_f32_e32 v237, v237, v238
	v_cvt_pk_bf16_f32 v237, v237, s0
	ds_write_b16 v207, v237 offset:1280
.LBB0_264:
	v_add_f32_e32 v236, v236, v44
	v_sub_f32_e32 v44, v236, v36
	v_mul_f32_e32 v44, 0x3fb8aa3b, v44
	v_exp_f32_e32 v237, v44
	ds_read_u16 v44, v208 offset:17920
	s_and_b64 vcc, exec, s[84:85]
	v_rcp_f32_e32 v238, v237
	s_waitcnt lgkmcnt(0)
	v_lshlrev_b32_e32 v44, 16, v44
	v_mul_f32_e32 v44, v238, v44
	v_cvt_pk_bf16_f32 v238, v44, s0
	ds_write_b16 v208, v238 offset:17920
	s_cbranch_vccnz .LBB0_266
	ds_read_u16 v238, v208 offset:1536
	s_waitcnt lgkmcnt(0)
	v_lshlrev_b32_e32 v238, 16, v238
	v_mul_f32_e32 v237, v237, v238
	v_cvt_pk_bf16_f32 v237, v237, s0
	ds_write_b16 v208, v237 offset:1536
.LBB0_266:
	v_add_f32_e32 v43, v236, v43
	v_sub_f32_e32 v236, v43, v36
	v_mul_f32_e32 v236, 0x3fb8aa3b, v236
	v_exp_f32_e32 v237, v236
	ds_read_u16 v236, v209 offset:18176
	s_and_b64 vcc, exec, s[84:85]
	v_rcp_f32_e32 v238, v237
	s_waitcnt lgkmcnt(0)
	v_lshlrev_b32_e32 v236, 16, v236
	v_mul_f32_e32 v236, v238, v236
	v_cvt_pk_bf16_f32 v238, v236, s0
	ds_write_b16 v209, v238 offset:18176
	s_cbranch_vccnz .LBB0_268
	ds_read_u16 v238, v209 offset:1792
	s_waitcnt lgkmcnt(0)
	v_lshlrev_b32_e32 v238, 16, v238
	v_mul_f32_e32 v237, v237, v238
	v_cvt_pk_bf16_f32 v237, v237, s0
	ds_write_b16 v209, v237 offset:1792
.LBB0_268:
	v_cvt_pk_bf16_f32 v238, v32, v33
	v_add_f32_e32 v33, v43, v42
	v_sub_f32_e32 v32, v33, v36
	v_mul_f32_e32 v32, 0x3fb8aa3b, v32
	v_cvt_pk_bf16_f32 v239, v132, v47
	v_cvt_pk_bf16_f32 v240, v46, v45
	v_cvt_pk_bf16_f32 v241, v44, v236
	v_exp_f32_e32 v42, v32
	ds_write_b128 v143, v[238:241]
	ds_read_u16 v32, v210 offset:18432
	s_and_b64 vcc, exec, s[84:85]
	v_rcp_f32_e32 v43, v42
	s_waitcnt lgkmcnt(0)
	v_lshlrev_b32_e32 v32, 16, v32
	v_mul_f32_e32 v32, v43, v32
	v_cvt_pk_bf16_f32 v43, v32, s0
	ds_write_b16 v210, v43 offset:18432
	s_cbranch_vccnz .LBB0_270
	ds_read_u16 v43, v210 offset:2048
	s_waitcnt lgkmcnt(0)
	v_lshlrev_b32_e32 v43, 16, v43
	v_mul_f32_e32 v42, v42, v43
	v_cvt_pk_bf16_f32 v42, v42, s0
	ds_write_b16 v210, v42 offset:2048
.LBB0_270:
	v_add_f32_e32 v41, v33, v41
	v_sub_f32_e32 v33, v41, v36
	v_mul_f32_e32 v33, 0x3fb8aa3b, v33
	v_exp_f32_e32 v42, v33
	ds_read_u16 v33, v211 offset:18688
	s_and_b64 vcc, exec, s[84:85]
	v_rcp_f32_e32 v43, v42
	s_waitcnt lgkmcnt(0)
	v_lshlrev_b32_e32 v33, 16, v33
	v_mul_f32_e32 v33, v43, v33
	v_cvt_pk_bf16_f32 v43, v33, s0
	ds_write_b16 v211, v43 offset:18688
	s_cbranch_vccnz .LBB0_272
	ds_read_u16 v43, v211 offset:2304
	s_waitcnt lgkmcnt(0)
	v_lshlrev_b32_e32 v43, 16, v43
	v_mul_f32_e32 v42, v42, v43
	v_cvt_pk_bf16_f32 v42, v42, s0
	ds_write_b16 v211, v42 offset:2304
.LBB0_272:
	v_add_f32_e32 v41, v41, v40
	v_sub_f32_e32 v40, v41, v36
	v_mul_f32_e32 v40, 0x3fb8aa3b, v40
	v_exp_f32_e32 v42, v40
	ds_read_u16 v40, v212 offset:18944
	s_and_b64 vcc, exec, s[84:85]
	v_rcp_f32_e32 v43, v42
	s_waitcnt lgkmcnt(0)
	v_lshlrev_b32_e32 v40, 16, v40
	v_mul_f32_e32 v40, v43, v40
	v_cvt_pk_bf16_f32 v43, v40, s0
	ds_write_b16 v212, v43 offset:18944
	s_cbranch_vccnz .LBB0_274
	ds_read_u16 v43, v212 offset:2560
	s_waitcnt lgkmcnt(0)
	v_lshlrev_b32_e32 v43, 16, v43
	v_mul_f32_e32 v42, v42, v43
	v_cvt_pk_bf16_f32 v42, v42, s0
	ds_write_b16 v212, v42 offset:2560
.LBB0_274:
	v_add_f32_e32 v41, v41, v39
	v_sub_f32_e32 v39, v41, v36
	v_mul_f32_e32 v39, 0x3fb8aa3b, v39
	v_exp_f32_e32 v42, v39
	ds_read_u16 v39, v213 offset:19200
	s_and_b64 vcc, exec, s[84:85]
	v_rcp_f32_e32 v43, v42
	s_waitcnt lgkmcnt(0)
	v_lshlrev_b32_e32 v39, 16, v39
	v_mul_f32_e32 v39, v43, v39
	v_cvt_pk_bf16_f32 v43, v39, s0
	ds_write_b16 v213, v43 offset:19200
	s_cbranch_vccnz .LBB0_276
	ds_read_u16 v43, v213 offset:2816
	s_waitcnt lgkmcnt(0)
	v_lshlrev_b32_e32 v43, 16, v43
	v_mul_f32_e32 v42, v42, v43
	v_cvt_pk_bf16_f32 v42, v42, s0
	ds_write_b16 v213, v42 offset:2816
.LBB0_276:
	v_add_f32_e32 v41, v41, v38
	v_sub_f32_e32 v38, v41, v36
	v_mul_f32_e32 v38, 0x3fb8aa3b, v38
	v_exp_f32_e32 v42, v38
	ds_read_u16 v38, v214 offset:19456
	s_and_b64 vcc, exec, s[84:85]
	v_rcp_f32_e32 v43, v42
	s_waitcnt lgkmcnt(0)
	v_lshlrev_b32_e32 v38, 16, v38
	v_mul_f32_e32 v38, v43, v38
	v_cvt_pk_bf16_f32 v43, v38, s0
	ds_write_b16 v214, v43 offset:19456
	s_cbranch_vccnz .LBB0_278
	ds_read_u16 v43, v214 offset:3072
	s_waitcnt lgkmcnt(0)
	v_lshlrev_b32_e32 v43, 16, v43
	v_mul_f32_e32 v42, v42, v43
	v_cvt_pk_bf16_f32 v42, v42, s0
	ds_write_b16 v214, v42 offset:3072
.LBB0_278:
	v_add_f32_e32 v41, v41, v37
	v_sub_f32_e32 v37, v41, v36
	v_mul_f32_e32 v37, 0x3fb8aa3b, v37
	v_exp_f32_e32 v42, v37
	ds_read_u16 v37, v215 offset:19712
	s_and_b64 vcc, exec, s[84:85]
	v_rcp_f32_e32 v43, v42
	s_waitcnt lgkmcnt(0)
	v_lshlrev_b32_e32 v37, 16, v37
	v_mul_f32_e32 v37, v43, v37
	v_cvt_pk_bf16_f32 v43, v37, s0
	ds_write_b16 v215, v43 offset:19712
	s_cbranch_vccnz .LBB0_280
	ds_read_u16 v43, v215 offset:3328
	s_waitcnt lgkmcnt(0)
	v_lshlrev_b32_e32 v43, 16, v43
	v_mul_f32_e32 v42, v42, v43
	v_cvt_pk_bf16_f32 v42, v42, s0
	ds_write_b16 v215, v42 offset:3328
.LBB0_280:
	v_add_f32_e32 v41, v41, v35
	v_sub_f32_e32 v35, v41, v36
	v_mul_f32_e32 v35, 0x3fb8aa3b, v35
	v_exp_f32_e32 v42, v35
	ds_read_u16 v35, v216 offset:19968
	s_and_b64 vcc, exec, s[84:85]
	v_rcp_f32_e32 v43, v42
	s_waitcnt lgkmcnt(0)
	v_lshlrev_b32_e32 v35, 16, v35
	v_mul_f32_e32 v35, v43, v35
	v_cvt_pk_bf16_f32 v43, v35, s0
	ds_write_b16 v216, v43 offset:19968
	s_cbranch_vccnz .LBB0_282
	ds_read_u16 v43, v216 offset:3584
	s_waitcnt lgkmcnt(0)
	v_lshlrev_b32_e32 v43, 16, v43
	v_mul_f32_e32 v42, v42, v43
	v_cvt_pk_bf16_f32 v42, v42, s0
	ds_write_b16 v216, v42 offset:3584
.LBB0_282:
	v_add_f32_e32 v34, v41, v34
	v_sub_f32_e32 v34, v34, v36
	v_mul_f32_e32 v34, 0x3fb8aa3b, v34
	v_exp_f32_e32 v36, v34
	ds_read_u16 v34, v217 offset:20224
	s_and_b64 vcc, exec, s[84:85]
	v_rcp_f32_e32 v41, v36
	s_waitcnt lgkmcnt(0)
	v_lshlrev_b32_e32 v34, 16, v34
	v_mul_f32_e32 v34, v41, v34
	v_cvt_pk_bf16_f32 v41, v34, s0
	ds_write_b16 v217, v41 offset:20224
	s_cbranch_vccnz .LBB0_284
	ds_read_u16 v41, v217 offset:3840
	s_waitcnt lgkmcnt(0)
	v_lshlrev_b32_e32 v41, 16, v41
	v_mul_f32_e32 v36, v36, v41
	v_cvt_pk_bf16_f32 v36, v36, s0
	ds_write_b16 v217, v36 offset:3840
.LBB0_284:
	v_cvt_pk_bf16_f32 v42, v32, v33
	v_cvt_pk_bf16_f32 v43, v40, v39
	v_cvt_pk_bf16_f32 v44, v38, v37
	v_cvt_pk_bf16_f32 v45, v35, v34
	ds_write_b128 v143, v[42:45] offset:16
	s_waitcnt lgkmcnt(0)
	s_barrier
	ds_read_b128 v[32:35], v114
	s_and_b64 vcc, exec, s[84:85]
	s_waitcnt lgkmcnt(0)
	v_pk_mul_f32 v[0:1], v[0:1], v[32:33]
	v_pk_mul_f32 v[2:3], v[2:3], v[34:35]
	s_cbranch_vccnz .LBB0_286
	v_cvt_pk_bf16_f32 v32, v0, v1
	v_cvt_pk_bf16_f32 v33, v2, v3
	v_add_u32_e32 v34, v113, v115
	ds_write_b64 v34, v[32:33] offset:49152

.Lhop_425:
	s_branch .LBB0_425
.LBB0_307:
	v_readlane_b32 s74, v249, 41
	v_readlane_b32 s76, v249, 43
	v_readlane_b32 s82, v249, 47
	v_readlane_b32 s84, v249, 49
	v_readlane_b32 s86, v249, 51
	v_readlane_b32 s88, v249, 53
	v_readlane_b32 s90, v249, 55
	v_readlane_b32 s66, v249, 39
	s_mov_b64 s[20:21], 0
	v_readlane_b32 s75, v249, 42
	v_readlane_b32 s77, v249, 44
	v_readlane_b32 s78, v249, 63
	v_readlane_b32 s79, v249, 45
	v_readlane_b32 s80, v249, 46
	v_readlane_b32 s83, v249, 48
	v_readlane_b32 s85, v249, 50
	v_readlane_b32 s87, v249, 52
	v_readlane_b32 s89, v249, 54
	v_readlane_b32 s91, v249, 56
	v_readlane_b32 s67, v249, 40
	s_movk_i32 s81, 0xf0

.LBB0_433:
	s_cmpk_gt_i32 s42, 0xbf
	s_mov_b64 s[20:21], -1
	s_cbranch_scc0 .LBB0_463
	s_cmpk_gt_u32 s42, 0xabf
	s_cbranch_scc0 .LBB0_460
	s_cmpk_gt_u32 s42, 0xdbf
	s_cbranch_scc0 .LBB0_457
	s_cmpk_gt_u32 s42, 0xfbf
	s_cbranch_scc0 .LBB0_454
	s_cmpk_gt_u32 s42, 0x10bf
	s_cbranch_scc0 .LBB0_449
	s_cmpk_gt_u32 s42, 0x10cf
	s_cbranch_scc0 .LBB0_446
	s_lshl_b32 s0, s42, 2
	s_addk_i32 s0, 0x3cc0
	s_and_b32 s20, s0, 0x3ffc
	s_cmpk_gt_u32 s42, 0x20cf
	s_movk_i32 s0, 0xa8
	s_cselect_b32 s0, s0, 0xa0
	s_add_u32 s0, s74, s0
	s_addc_u32 s1, s75, 0
	s_load_dwordx2 s[0:1], s[0:1], 0x0
	v_or_b32_e32 v29, s20, v19
	v_lshlrev_b32_e32 v132, 12, v29
	v_mov_b32_e32 v27, v133
	v_cmp_lt_i32_e32 vcc, v170, v169
	s_waitcnt lgkmcnt(0)
	v_lshl_add_u64 v[0:1], s[0:1], 0, v[132:133]
	v_lshl_add_u64 v[0:1], v[0:1], 0, v[26:27]
	global_load_dwordx4 v[34:37], v[0:1], off
	global_load_dwordx4 v[8:11], v[0:1], off offset:16
	global_load_dwordx4 v[4:7], v[0:1], off offset:32
	s_nop 0
	global_load_dwordx4 v[0:3], v[0:1], off offset:48
	v_cndmask_b32_e32 v27, v167, v170, vcc
	v_lshlrev_b32_e32 v27, 2, v27
	v_cmp_lt_i32_e32 vcc, v171, v169
	s_mov_b32 s20, 0x43c00000
	s_cmpk_lt_u32 s42, 0x20d0
	s_waitcnt vmcnt(0)
	v_max_f32_e64 v31, |v37|, |v37|
	v_max_f32_e64 v32, |v36|, |v36|
	v_max_f32_e64 v33, |v11|, |v11|
	v_max_f32_e64 v38, |v10|, |v10|
	v_max_f32_e64 v39, |v7|, |v7|
	v_max_f32_e64 v40, |v6|, |v6|
	v_max_f32_e64 v41, |v3|, |v3|
	v_max_f32_e64 v42, |v2|, |v2|
	v_max_f32_e32 v31, v32, v31
	v_max_f32_e32 v32, v38, v33
	v_max_f32_e32 v33, v40, v39
	v_max_f32_e32 v38, v42, v41
	v_max3_f32 v31, |v34|, |v35|, v31
	v_max3_f32 v32, |v8|, |v9|, v32
	v_max3_f32 v33, |v4|, |v5|, v33
	v_max3_f32 v38, |v0|, |v1|, v38
	v_max3_f32 v31, v31, 0, v32
	v_max3_f32 v31, v31, v33, v38
	ds_bpermute_b32 v27, v27, v31
	v_cndmask_b32_e32 v32, v167, v171, vcc
	v_lshlrev_b32_e32 v32, 2, v32
	v_cmp_lt_i32_e32 vcc, v172, v169
	s_waitcnt lgkmcnt(0)
	v_max_f32_e32 v27, v27, v27
	v_max_f32_e32 v27, v31, v27
	ds_bpermute_b32 v31, v32, v27
	v_cndmask_b32_e32 v32, v167, v172, vcc
	v_lshlrev_b32_e32 v32, 2, v32
	v_cmp_lt_i32_e32 vcc, v173, v169
	s_waitcnt lgkmcnt(0)
	v_max_f32_e32 v31, v31, v31
	v_max_f32_e32 v27, v27, v31
	ds_bpermute_b32 v31, v32, v27
	v_cndmask_b32_e32 v32, v167, v173, vcc
	v_lshlrev_b32_e32 v32, 2, v32
	v_cmp_lt_i32_e32 vcc, v174, v169
	s_waitcnt lgkmcnt(0)
	v_max_f32_e32 v31, v31, v31
	v_max_f32_e32 v27, v27, v31
	ds_bpermute_b32 v31, v32, v27
	v_cndmask_b32_e32 v32, v167, v174, vcc
	v_lshlrev_b32_e32 v32, 2, v32
	v_cmp_lt_i32_e32 vcc, v175, v169
	s_waitcnt lgkmcnt(0)
	v_max_f32_e32 v31, v31, v31
	v_max_f32_e32 v27, v27, v31
	ds_bpermute_b32 v31, v32, v27
	v_cndmask_b32_e32 v32, v167, v175, vcc
	v_lshlrev_b32_e32 v32, 2, v32
	s_waitcnt lgkmcnt(0)
	v_max_f32_e32 v31, v31, v31
	v_max_f32_e32 v27, v27, v31
	ds_bpermute_b32 v31, v32, v27
	s_waitcnt lgkmcnt(0)
	v_max_f32_e32 v31, v31, v31
	v_max_f32_e32 v27, v27, v31
	v_div_scale_f32 v31, s[0:1], v27, v27, s20
	v_rcp_f32_e32 v32, v31
	v_div_scale_f32 v33, vcc, s20, v27, s20
	v_cmp_lt_f32_e64 s[40:41], 0, v27
	v_fma_f32 v38, -v31, v32, 1.0
	v_fmac_f32_e32 v32, v38, v32
	v_mul_f32_e32 v38, v33, v32
	v_fma_f32 v39, -v31, v38, v33
	v_fmac_f32_e32 v38, v39, v32
	v_fma_f32 v31, -v31, v38, v33
	v_div_fmas_f32 v31, v31, v32, v38
	v_div_fixup_f32 v31, v31, v27, s20
	v_cndmask_b32_e64 v31, 1.0, v31, s[40:41]
	v_mul_f32_e32 v32, v34, v31
	v_mul_f32_e32 v33, v35, v31
	v_mov_b32_e32 v34, v133
	v_cvt_pk_fp8_f32 v34, v32, v33
	v_mul_f32_e32 v32, v36, v31
	v_mul_f32_e32 v33, v37, v31
	s_mov_b64 s[20:21], -1
	v_cvt_pk_fp8_f32 v34, v32, v33 op_sel:[0,0,1]
	s_cbranch_scc0 .LBB0_441
	v_lshlrev_b32_e32 v132, 7, v29
	v_lshl_add_u64 v[32:33], v[14:15], 0, v[132:133]
	s_mov_b32 s34, 0xfe000000
	s_mov_b32 s35, -1
	v_lshl_add_u64 v[32:33], v[32:33], 0, s[34:35]
	global_store_dword v[32:33], v34, off
	s_mov_b64 s[20:21], 0

.LBB0_469:
	v_readlane_b32 s0, v251, 0
	s_cmp_eq_u32 s78, 26
	s_cselect_b32 s1, 1, 0
	s_cmp_lt_u32 s0, 2
	s_cselect_b32 s20, 1, 0
	s_and_b32 s1, s1, s20
	s_add_i32 s0, s0, s1
	v_writelane_b32 v251, s0, 0
	s_xor_b32 s1, s1, 1
	s_add_i32 s78, s78, s1
	v_cmp_lt_i32_e32 vcc, s78, v162
	s_mov_b64 s[20:21], -1
	s_and_saveexec_b64 s[30:31], vcc
	v_readlane_b32 s34, v249, 57
	v_readlane_b32 s35, v249, 58
	s_cbranch_execnz .LBB0_470
	s_getpc_b64 s[98:99]

	.amdhsa_kernel _Z4mega6Params
		.amdhsa_group_segment_fixed_size 0
		.amdhsa_private_segment_fixed_size 0
		.amdhsa_kernarg_size 464
		.amdhsa_user_sgpr_count 2
		.amdhsa_user_sgpr_dispatch_ptr 0
		.amdhsa_user_sgpr_queue_ptr 0
		.amdhsa_user_sgpr_kernarg_segment_ptr 1
		.amdhsa_user_sgpr_dispatch_id 0
		.amdhsa_user_sgpr_kernarg_preload_length 0
		.amdhsa_user_sgpr_kernarg_preload_offset 0
		.amdhsa_user_sgpr_private_segment_size 0
		.amdhsa_uses_dynamic_stack 0
		.amdhsa_enable_private_segment 0
		.amdhsa_system_sgpr_workgroup_id_x 1
		.amdhsa_system_sgpr_workgroup_id_y 0
		.amdhsa_system_sgpr_workgroup_id_z 0
		.amdhsa_system_sgpr_workgroup_info 0
		.amdhsa_system_vgpr_workitem_id 2
		.amdhsa_next_free_vgpr 252
		.amdhsa_next_free_sgpr 100
		.amdhsa_accum_offset 252
		.amdhsa_reserve_vcc 1
		.amdhsa_float_round_mode_32 0
		.amdhsa_float_round_mode_16_64 0
		.amdhsa_float_denorm_mode_32 3
		.amdhsa_float_denorm_mode_16_64 3
		.amdhsa_dx10_clamp 1
		.amdhsa_ieee_mode 1
		.amdhsa_fp16_overflow 0
		.amdhsa_tg_split 0
		.amdhsa_exception_fp_ieee_invalid_op 0
		.amdhsa_exception_fp_denorm_src 0
		.amdhsa_exception_fp_ieee_div_zero 0
		.amdhsa_exception_fp_ieee_overflow 0
		.amdhsa_exception_fp_ieee_underflow 0
		.amdhsa_exception_fp_ieee_inexact 0
		.amdhsa_exception_int_div_zero 0
	.end_amdhsa_kernel

amdhsa.kernels:
  - .agpr_count:     0
    .args:
      - .offset:         0
        .size:           208
        .value_kind:     by_value
      - .offset:         208
        .size:           4
        .value_kind:     hidden_block_count_x
      - .offset:         212
        .size:           4
        .value_kind:     hidden_block_count_y
      - .offset:         216
        .size:           4
        .value_kind:     hidden_block_count_z
      - .offset:         220
        .size:           2
        .value_kind:     hidden_group_size_x
      - .offset:         222
        .size:           2
        .value_kind:     hidden_group_size_y
      - .offset:         224
        .size:           2
        .value_kind:     hidden_group_size_z
      - .offset:         226
        .size:           2
        .value_kind:     hidden_remainder_x
      - .offset:         228
        .size:           2
        .value_kind:     hidden_remainder_y
      - .offset:         230
        .size:           2
        .value_kind:     hidden_remainder_z
      - .offset:         248
        .size:           8
        .value_kind:     hidden_global_offset_x
      - .offset:         256
        .size:           8
        .value_kind:     hidden_global_offset_y
      - .offset:         264
        .size:           8
        .value_kind:     hidden_global_offset_z
      - .offset:         272
        .size:           2
        .value_kind:     hidden_grid_dims
      - .offset:         296
        .size:           8
        .value_kind:     hidden_multigrid_sync_arg
      - .offset:         328
        .size:           4
        .value_kind:     hidden_dynamic_lds_size
    .group_segment_fixed_size: 0
    .kernarg_segment_align: 8
    .kernarg_segment_size: 464
    .language:       OpenCL C
    .language_version:
      - 2
      - 0
    .max_flat_workgroup_size: 512
    .name:           _Z4mega6Params
    .private_segment_fixed_size: 0
    .sgpr_count:     106
    .sgpr_spill_count: 137
    .symbol:         _Z4mega6Params.kd
    .uniform_work_group_size: 1
    .uses_dynamic_stack: false
    .vgpr_count:     252
    .vgpr_spill_count: 0
    .wavefront_size: 64
